# combined v45 + attention waves 4-7 stagger s_sleep 2 per unit
# speedup vs baseline: 1.0007x; 1.0007x over previous
; #define LAS __attribute__((address_space(3)))
; __device__ __forceinline__ void attn_phase(LAS unsigned char* lds, const bf16_t* Q, const bf16_t* Kb, const bf16_t* Vt, bf16_t* AO, const float* sink, const float* qg, const float* kg) {
;     ...
;         __syncthreads();
; #pragma unroll
;         for (int it = 0; it < 6; ++it) { const int idx = it * NTHR + tid, row = idx >> 3, ch = idx & 7; *(LAS u32x4*)(Kl + row * KROW + ch * 16) = kreg[it]; }
; #pragma unroll
;         for (int it = 0; it < 6; ++it) { const int idx = it * NTHR + tid, d = idx / 48, ch = idx % 48; LAS u32x2* pp = (LAS u32x2*)(Vl + d * VROW + ch * 16); pp[0] = (u32x2){vreg[it].x, vreg[it].y}; pp[1] = (u32x2){vreg[it].z, vreg[it].w}; }
;         __syncthreads();
;         if (uid + G < 1024) ATT_LOAD(uid + G);
.LBB0_147:
	v_readlane_b32 s0, v255, 39
	s_add_i32 s41, s6, s0
	s_cmpk_gt_i32 s41, 0x3ff
	s_cselect_b64 s[28:29], -1, 0
	s_and_b64 vcc, exec, s[28:29]
	s_barrier
	s_waitcnt vmcnt(0)
	ds_write_b128 v247, v[116:119]
	ds_write_b128 v248, v[112:115]
	ds_write_b128 v249, v[120:123]
	ds_write_b128 v250, v[124:127]
	ds_write_b128 v251, v[128:131]
	ds_write_b128 v233, v[132:135]
	ds_write2_b64 v237, v[136:137], v[138:139] offset1:1
	ds_write2_b64 v202, v[140:141], v[142:143] offset1:1
	ds_write2_b64 v203, v[144:145], v[146:147] offset1:1
	ds_write2_b64 v204, v[148:149], v[150:151] offset1:1
	ds_write2_b64 v205, v[152:153], v[154:155] offset1:1
	ds_write2_b64 v231, v[156:157], v[158:159] offset1:1
	s_waitcnt lgkmcnt(0)
	s_barrier
	s_bitcmp1_b32 s32, 8
	s_cbranch_scc0 .Lattn_nostag
	s_sleep 2
